# v16: CMP2 tile in phase-2 tail + hand-written CMP2 epilogue (per-lane bases, immediate offsets, paired bf16 stores)
# speedup vs baseline: 1.2141x; 1.0090x over previous
.LBB0_920:
	s_waitcnt lgkmcnt(0)
	s_barrier
	v_cmp_eq_u32_e64 s[6:7], 0, v173
	s_and_saveexec_b64 s[8:9], s[6:7]
	s_cbranch_execz .Lc2e_done
	v_and_b32_e32 v64, 31, v166
	v_bfe_u32 v65, v166, 5, 1
	s_lshr_b32 s1, s0, 7
	s_and_b32 s2, s1, 1
	s_lshl_b32 s2, s2, 6
	v_lshlrev_b32_e32 v66, 5, v172
	v_lshl_add_u32 v66, v65, 1, v66
	v_add_u32_e32 v66, s2, v66
	s_and_b32 s1, s1, 14
	s_lshl_b32 s1, s1, 14
	v_mov_b32_e32 v67, 0x62
	v_cmp_eq_u32_e64 s[10:11], v67, v66
	v_lshlrev_b32_e32 v74, 7, v66
	v_lshl_add_u32 v74, v64, 1, v74
	v_add_u32_e32 v74, s1, v74
	v_mov_b32_e32 v75, 0
	v_lshlrev_b32_e32 v76, 8, v64
	v_lshl_add_u32 v76, v66, 1, v76
	v_add_u32_e32 v76, s1, v76
	v_mov_b32_e32 v77, 0
	s_mov_b32 s2, 0x4000
	s_mov_b32 s3, 0
	s_and_b64 vcc, exec, s[14:15]
	s_cbranch_vccnz .Lc2e_v
	v_lshl_add_u64 v[70:71], s[52:53], 0, v[74:75]
	s_branch .Lc2e_kv
.Lc2e_v:
	v_lshl_add_u64 v[70:71], s[54:55], 0, v[74:75]
.Lc2e_kv:
	v_lshl_add_u64 v[72:73], v[70:71], 0, s[2:3]
	s_and_b64 vcc, exec, s[14:15]
	s_cbranch_vccnz .Lc2e_vbody
	v_cvt_pk_bf16_f32 v80, v48, v49
	global_store_short v[70:71], v80, off
	global_store_short_d16_hi v[72:73], v80, off
	v_cvt_pk_bf16_f32 v81, v50, v51
	global_store_short v[70:71], v81, off offset:128
	global_store_short_d16_hi v[72:73], v81, off offset:128
	v_cvt_pk_bf16_f32 v82, v52, v53
	global_store_short v[70:71], v82, off offset:512
	global_store_short_d16_hi v[72:73], v82, off offset:512
	v_cvt_pk_bf16_f32 v83, v54, v55
	global_store_short v[70:71], v83, off offset:640
	global_store_short_d16_hi v[72:73], v83, off offset:640
	v_cvt_pk_bf16_f32 v84, v56, v57
	global_store_short v[70:71], v84, off offset:1024
	global_store_short_d16_hi v[72:73], v84, off offset:1024
	v_cvt_pk_bf16_f32 v85, v58, v59
	global_store_short v[70:71], v85, off offset:1152
	global_store_short_d16_hi v[72:73], v85, off offset:1152
	v_cvt_pk_bf16_f32 v86, v60, v61
	global_store_short v[70:71], v86, off offset:1536
	global_store_short_d16_hi v[72:73], v86, off offset:1536
	v_cvt_pk_bf16_f32 v87, v62, v63
	global_store_short v[70:71], v87, off offset:1664
	global_store_short_d16_hi v[72:73], v87, off offset:1664
	v_cvt_pk_bf16_f32 v88, v32, v33
	global_store_short v[70:71], v88, off offset:64
	global_store_short_d16_hi v[72:73], v88, off offset:64
	v_cvt_pk_bf16_f32 v89, v34, v35
	global_store_short v[70:71], v89, off offset:192
	global_store_short_d16_hi v[72:73], v89, off offset:192
	v_cvt_pk_bf16_f32 v90, v36, v37
	global_store_short v[70:71], v90, off offset:576
	global_store_short_d16_hi v[72:73], v90, off offset:576
	v_cvt_pk_bf16_f32 v91, v38, v39
	global_store_short v[70:71], v91, off offset:704
	global_store_short_d16_hi v[72:73], v91, off offset:704
	v_cvt_pk_bf16_f32 v92, v40, v41
	global_store_short v[70:71], v92, off offset:1088
	global_store_short_d16_hi v[72:73], v92, off offset:1088
	v_cvt_pk_bf16_f32 v93, v42, v43
	global_store_short v[70:71], v93, off offset:1216
	global_store_short_d16_hi v[72:73], v93, off offset:1216
	v_cvt_pk_bf16_f32 v94, v44, v45
	global_store_short v[70:71], v94, off offset:1600
	global_store_short_d16_hi v[72:73], v94, off offset:1600
	v_cvt_pk_bf16_f32 v95, v46, v47
	global_store_short v[70:71], v95, off offset:1728
	global_store_short_d16_hi v[72:73], v95, off offset:1728
	v_cvt_pk_bf16_f32 v80, v16, v17
	global_store_short v[70:71], v80, off offset:2048
	global_store_short_d16_hi v[72:73], v80, off offset:2048
	v_cvt_pk_bf16_f32 v81, v18, v19
	global_store_short v[70:71], v81, off offset:2176
	global_store_short_d16_hi v[72:73], v81, off offset:2176
	v_cvt_pk_bf16_f32 v82, v20, v21
	global_store_short v[70:71], v82, off offset:2560
	global_store_short_d16_hi v[72:73], v82, off offset:2560
	v_cvt_pk_bf16_f32 v83, v22, v23
	global_store_short v[70:71], v83, off offset:2688
	global_store_short_d16_hi v[72:73], v83, off offset:2688
	v_cvt_pk_bf16_f32 v84, v24, v25
	global_store_short v[70:71], v84, off offset:3072
	global_store_short_d16_hi v[72:73], v84, off offset:3072
	v_cvt_pk_bf16_f32 v85, v26, v27
	global_store_short v[70:71], v85, off offset:3200
	global_store_short_d16_hi v[72:73], v85, off offset:3200
	v_cvt_pk_bf16_f32 v86, v28, v29
	global_store_short v[70:71], v86, off offset:3584
	global_store_short_d16_hi v[72:73], v86, off offset:3584
	v_cvt_pk_bf16_f32 v87, v30, v31
	v_cndmask_b32_e64 v87, v87, 0, s[10:11]
	global_store_short v[70:71], v87, off offset:3712
	global_store_short_d16_hi v[72:73], v87, off offset:3712
	v_cvt_pk_bf16_f32 v88, v0, v1
	global_store_short v[70:71], v88, off offset:2112
	global_store_short_d16_hi v[72:73], v88, off offset:2112
	v_cvt_pk_bf16_f32 v89, v2, v3
	global_store_short v[70:71], v89, off offset:2240
	global_store_short_d16_hi v[72:73], v89, off offset:2240
	v_cvt_pk_bf16_f32 v90, v4, v5
	global_store_short v[70:71], v90, off offset:2624
	global_store_short_d16_hi v[72:73], v90, off offset:2624
	v_cvt_pk_bf16_f32 v91, v6, v7
	global_store_short v[70:71], v91, off offset:2752
	global_store_short_d16_hi v[72:73], v91, off offset:2752
	v_cvt_pk_bf16_f32 v92, v8, v9
	global_store_short v[70:71], v92, off offset:3136
	global_store_short_d16_hi v[72:73], v92, off offset:3136
	v_cvt_pk_bf16_f32 v93, v10, v11
	global_store_short v[70:71], v93, off offset:3264
	global_store_short_d16_hi v[72:73], v93, off offset:3264
	v_cvt_pk_bf16_f32 v94, v12, v13
	global_store_short v[70:71], v94, off offset:3648
	global_store_short_d16_hi v[72:73], v94, off offset:3648
	v_cvt_pk_bf16_f32 v95, v14, v15
	v_cndmask_b32_e64 v95, v95, 0, s[10:11]
	global_store_short v[70:71], v95, off offset:3776
	global_store_short_d16_hi v[72:73], v95, off offset:3776
	s_branch .Lc2e_done
.Lc2e_vbody:
	v_lshl_add_u64 v[100:101], s[56:57], 0, v[76:77]
	v_lshl_add_u64 v[102:103], v[100:101], 0, s[2:3]
	s_mov_b32 s2, 0x2000
	v_lshl_add_u64 v[104:105], v[100:101], 0, s[2:3]
	v_lshl_add_u64 v[106:107], v[102:103], 0, s[2:3]
	v_cvt_pk_bf16_f32 v80, v48, v49
	global_store_short v[70:71], v80, off
	global_store_short_d16_hi v[72:73], v80, off
	global_store_short v[100:101], v80, off
	global_store_short_d16_hi v[102:103], v80, off
	v_cvt_pk_bf16_f32 v81, v50, v51
	global_store_short v[70:71], v81, off offset:128
	global_store_short_d16_hi v[72:73], v81, off offset:128
	global_store_short v[100:101], v81, off offset:2
	global_store_short_d16_hi v[102:103], v81, off offset:2
	v_cvt_pk_bf16_f32 v82, v52, v53
	global_store_short v[70:71], v82, off offset:512
	global_store_short_d16_hi v[72:73], v82, off offset:512
	global_store_short v[100:101], v82, off offset:8
	global_store_short_d16_hi v[102:103], v82, off offset:8
	v_cvt_pk_bf16_f32 v83, v54, v55
	global_store_short v[70:71], v83, off offset:640
	global_store_short_d16_hi v[72:73], v83, off offset:640
	global_store_short v[100:101], v83, off offset:10
	global_store_short_d16_hi v[102:103], v83, off offset:10
	v_cvt_pk_bf16_f32 v84, v56, v57
	global_store_short v[70:71], v84, off offset:1024
	global_store_short_d16_hi v[72:73], v84, off offset:1024
	global_store_short v[100:101], v84, off offset:16
	global_store_short_d16_hi v[102:103], v84, off offset:16
	v_cvt_pk_bf16_f32 v85, v58, v59
	global_store_short v[70:71], v85, off offset:1152
	global_store_short_d16_hi v[72:73], v85, off offset:1152
	global_store_short v[100:101], v85, off offset:18
	global_store_short_d16_hi v[102:103], v85, off offset:18
	v_cvt_pk_bf16_f32 v86, v60, v61
	global_store_short v[70:71], v86, off offset:1536
	global_store_short_d16_hi v[72:73], v86, off offset:1536
	global_store_short v[100:101], v86, off offset:24
	global_store_short_d16_hi v[102:103], v86, off offset:24
	v_cvt_pk_bf16_f32 v87, v62, v63
	global_store_short v[70:71], v87, off offset:1664
	global_store_short_d16_hi v[72:73], v87, off offset:1664
	global_store_short v[100:101], v87, off offset:26
	global_store_short_d16_hi v[102:103], v87, off offset:26
	v_cvt_pk_bf16_f32 v88, v32, v33
	global_store_short v[70:71], v88, off offset:64
	global_store_short_d16_hi v[72:73], v88, off offset:64
	global_store_short v[104:105], v88, off
	global_store_short_d16_hi v[106:107], v88, off
	v_cvt_pk_bf16_f32 v89, v34, v35
	global_store_short v[70:71], v89, off offset:192
	global_store_short_d16_hi v[72:73], v89, off offset:192
	global_store_short v[104:105], v89, off offset:2
	global_store_short_d16_hi v[106:107], v89, off offset:2
	v_cvt_pk_bf16_f32 v90, v36, v37
	global_store_short v[70:71], v90, off offset:576
	global_store_short_d16_hi v[72:73], v90, off offset:576
	global_store_short v[104:105], v90, off offset:8
	global_store_short_d16_hi v[106:107], v90, off offset:8
	v_cvt_pk_bf16_f32 v91, v38, v39
	global_store_short v[70:71], v91, off offset:704
	global_store_short_d16_hi v[72:73], v91, off offset:704
	global_store_short v[104:105], v91, off offset:10
	global_store_short_d16_hi v[106:107], v91, off offset:10
	v_cvt_pk_bf16_f32 v92, v40, v41
	global_store_short v[70:71], v92, off offset:1088
	global_store_short_d16_hi v[72:73], v92, off offset:1088
	global_store_short v[104:105], v92, off offset:16
	global_store_short_d16_hi v[106:107], v92, off offset:16
	v_cvt_pk_bf16_f32 v93, v42, v43
	global_store_short v[70:71], v93, off offset:1216
	global_store_short_d16_hi v[72:73], v93, off offset:1216
	global_store_short v[104:105], v93, off offset:18
	global_store_short_d16_hi v[106:107], v93, off offset:18
	v_cvt_pk_bf16_f32 v94, v44, v45
	global_store_short v[70:71], v94, off offset:1600
	global_store_short_d16_hi v[72:73], v94, off offset:1600
	global_store_short v[104:105], v94, off offset:24
	global_store_short_d16_hi v[106:107], v94, off offset:24
	v_cvt_pk_bf16_f32 v95, v46, v47
	global_store_short v[70:71], v95, off offset:1728
	global_store_short_d16_hi v[72:73], v95, off offset:1728
	global_store_short v[104:105], v95, off offset:26
	global_store_short_d16_hi v[106:107], v95, off offset:26
	v_cvt_pk_bf16_f32 v80, v16, v17
	global_store_short v[70:71], v80, off offset:2048
	global_store_short_d16_hi v[72:73], v80, off offset:2048
	global_store_short v[100:101], v80, off offset:32
	global_store_short_d16_hi v[102:103], v80, off offset:32
	v_cvt_pk_bf16_f32 v81, v18, v19
	global_store_short v[70:71], v81, off offset:2176
	global_store_short_d16_hi v[72:73], v81, off offset:2176
	global_store_short v[100:101], v81, off offset:34
	global_store_short_d16_hi v[102:103], v81, off offset:34
	v_cvt_pk_bf16_f32 v82, v20, v21
	global_store_short v[70:71], v82, off offset:2560
	global_store_short_d16_hi v[72:73], v82, off offset:2560
	global_store_short v[100:101], v82, off offset:40
	global_store_short_d16_hi v[102:103], v82, off offset:40
	v_cvt_pk_bf16_f32 v83, v22, v23
	global_store_short v[70:71], v83, off offset:2688
	global_store_short_d16_hi v[72:73], v83, off offset:2688
	global_store_short v[100:101], v83, off offset:42
	global_store_short_d16_hi v[102:103], v83, off offset:42
	v_cvt_pk_bf16_f32 v84, v24, v25
	global_store_short v[70:71], v84, off offset:3072
	global_store_short_d16_hi v[72:73], v84, off offset:3072
	global_store_short v[100:101], v84, off offset:48
	global_store_short_d16_hi v[102:103], v84, off offset:48
	v_cvt_pk_bf16_f32 v85, v26, v27
	global_store_short v[70:71], v85, off offset:3200
	global_store_short_d16_hi v[72:73], v85, off offset:3200
	global_store_short v[100:101], v85, off offset:50
	global_store_short_d16_hi v[102:103], v85, off offset:50
	v_cvt_pk_bf16_f32 v86, v28, v29
	global_store_short v[70:71], v86, off offset:3584
	global_store_short_d16_hi v[72:73], v86, off offset:3584
	global_store_short v[100:101], v86, off offset:56
	global_store_short_d16_hi v[102:103], v86, off offset:56
	v_cvt_pk_bf16_f32 v87, v30, v31
	v_cndmask_b32_e64 v87, v87, 0, s[10:11]
	global_store_short v[70:71], v87, off offset:3712
	global_store_short_d16_hi v[72:73], v87, off offset:3712
	global_store_short v[100:101], v87, off offset:58
	global_store_short_d16_hi v[102:103], v87, off offset:58
	v_cvt_pk_bf16_f32 v88, v0, v1
	global_store_short v[70:71], v88, off offset:2112
	global_store_short_d16_hi v[72:73], v88, off offset:2112
	global_store_short v[104:105], v88, off offset:32
	global_store_short_d16_hi v[106:107], v88, off offset:32
	v_cvt_pk_bf16_f32 v89, v2, v3
	global_store_short v[70:71], v89, off offset:2240
	global_store_short_d16_hi v[72:73], v89, off offset:2240
	global_store_short v[104:105], v89, off offset:34
	global_store_short_d16_hi v[106:107], v89, off offset:34
	v_cvt_pk_bf16_f32 v90, v4, v5
	global_store_short v[70:71], v90, off offset:2624
	global_store_short_d16_hi v[72:73], v90, off offset:2624
	global_store_short v[104:105], v90, off offset:40
	global_store_short_d16_hi v[106:107], v90, off offset:40
	v_cvt_pk_bf16_f32 v91, v6, v7
	global_store_short v[70:71], v91, off offset:2752
	global_store_short_d16_hi v[72:73], v91, off offset:2752
	global_store_short v[104:105], v91, off offset:42
	global_store_short_d16_hi v[106:107], v91, off offset:42
	v_cvt_pk_bf16_f32 v92, v8, v9
	global_store_short v[70:71], v92, off offset:3136
	global_store_short_d16_hi v[72:73], v92, off offset:3136
	global_store_short v[104:105], v92, off offset:48
	global_store_short_d16_hi v[106:107], v92, off offset:48
	v_cvt_pk_bf16_f32 v93, v10, v11
	global_store_short v[70:71], v93, off offset:3264
	global_store_short_d16_hi v[72:73], v93, off offset:3264
	global_store_short v[104:105], v93, off offset:50
	global_store_short_d16_hi v[106:107], v93, off offset:50
	v_cvt_pk_bf16_f32 v94, v12, v13
	global_store_short v[70:71], v94, off offset:3648
	global_store_short_d16_hi v[72:73], v94, off offset:3648
	global_store_short v[104:105], v94, off offset:56
	global_store_short_d16_hi v[106:107], v94, off offset:56
	v_cvt_pk_bf16_f32 v95, v14, v15
	v_cndmask_b32_e64 v95, v95, 0, s[10:11]
	global_store_short v[70:71], v95, off offset:3776
	global_store_short_d16_hi v[72:73], v95, off offset:3776
	global_store_short v[104:105], v95, off offset:58
	global_store_short_d16_hi v[106:107], v95, off offset:58
.Lc2e_done:
	s_or_b64 exec, exec, s[8:9]
	s_waitcnt lgkmcnt(0)
	s_branch .LBB0_562

.LBB0_1486:
	s_endpgm
	.section	.rodata,"a",@progbits
	.p2align	6, 0x0
